# attention A: last cross-barrier V-fragment prefetch issued three MFMA gaps earlier (a K fragment moved to a free register quad)
# baseline (speedup 1.0000x reference)
; #define FLAS __attribute__((address_space(3)))
; #define FA_SB() __builtin_amdgcn_sched_barrier(0)
; #define FA_EXP2(J, PX, R) do { const float e0_ = __builtin_amdgcn_exp2f(PX[R]), e1_ = __builtin_amdgcn_exp2f(PX[(R) + 1]); ps += e0_; ps += e1_; PWN[(J) >> 2][(J) & 3] = cvtpk(e0_, e1_); } while (0)
; __device__ __forceinline__ void attn_unit_a(FLAS unsigned char* lds, const Unit u) {
;     ...
;         u32x4 vr[3];
; #pragma unroll
;         for (int m = 0; m < 3; ++m) vr[m] = FA_VFRAG(m);
;     ...
;         kf[0] = FA_KF(2, 0); kf[1] = FA_KF(2, 1); FA_EXP2(9, pC1, 2); FA_SB();
;         pN0 = __builtin_amdgcn_mfma_f32_32x32x16_bf16(kf[2], qr[1], pN0, 0, 0, 0); FA_EXP2(10, pC1, 4); FA_SB();
;         pN1 = __builtin_amdgcn_mfma_f32_32x32x16_bf16(kf[3], qr[1], pN1, 0, 0, 0); kf[2] = FA_KF(3, 0); kf[3] = FA_KF(3, 1); FA_EXP2(11, pC1, 6); FA_SB();
;         pN0 = __builtin_amdgcn_mfma_f32_32x32x16_bf16(kf[0], qr[2], pN0, 0, 0, 0); FA_EXP2(12, pC1, 8); FA_SB();
;         pN1 = __builtin_amdgcn_mfma_f32_32x32x16_bf16(kf[1], qr[2], pN1, 0, 0, 0); FA_EXP2(13, pC1, 10); FA_SB();
;         pN0 = __builtin_amdgcn_mfma_f32_32x32x16_bf16(kf[2], qr[3], pN0, 0, 0, 0); FA_EXP2(14, pC1, 12); FA_SB();
;         pN1 = __builtin_amdgcn_mfma_f32_32x32x16_bf16(kf[3], qr[3], pN1, 0, 0, 0); FA_EXP2(15, pC1, 14); FA_SB();
;     ...
;         lsum += ps; cbC = cbN;
;         if (i + 2 < NT) { *(FLAS u32x4*)(lds + LA_K + (i & 1) * KBUF + kdst) = kreg;
; #pragma unroll
;             for (int j = 0; j < 2; ++j) { *(FLAS u32x2*)(lds + LA_V + ((i + 2) & 3) * VBUF + vdst + j * 64 * VPITCH) = (u32x2){vreg[j].x, vreg[j].y}; *(FLAS u32x2*)(lds + LA_V + ((i + 2) & 3) * VBUF + vdst + j * 64 * VPITCH + 16) = (u32x2){vreg[j].z, vreg[j].w}; } }
.Lk2_e:
	ds_read_b128 v[128:131], v249 offset:8192
	ds_read_b128 v[132:135], v249 offset:8704
	s_add_i32 s34, s19, 2
	v_mfma_f32_32x32x16_bf16 v[64:79], v[196:199], v[164:167], v[64:79]
	v_exp_f32_e32 v116, v116
	v_exp_f32_e32 v117, v117
	v_mfma_f32_32x32x16_bf16 v[80:95], v[192:195], v[164:167], v[80:95]
	s_and_b32 s0, s34, 2
	s_mulk_i32 s0, 0x4800
	v_add_u32_e32 v188, s0, v245
	v_add_u32_e32 v189, 0x4000, v188
	v_add_u32_e32 v188, 0x6000, v188
	s_waitcnt vmcnt(2)
	ds_write_b128 v225, v[176:179]
	s_waitcnt vmcnt(1)
	ds_write2_b64 v189, v[180:181], v[182:183] offset1:2
	s_waitcnt vmcnt(0)
	ds_write2_b64 v188, v[184:185], v[186:187] offset0:128 offset1:130
	s_and_b32 s0, s19, 2
	s_mulk_i32 s0, 0x4800
	v_add_u32_e32 v201, s0, v251
	ds_read_b128 v[188:191], v250 offset:8192
	ds_read_b128 v[140:143], v250 offset:8704
	ds_read_b128 v[136:139], v201 offset:25600
	v_exp_f32_e32 v118, v118
	v_exp_f32_e32 v119, v119
	s_waitcnt lgkmcnt(6)
	v_mfma_f32_32x32x16_bf16 v[64:79], v[128:131], v[168:171], v[64:79]
	ds_read_b128 v[128:131], v201 offset:16384
	v_exp_f32_e32 v120, v120
	v_exp_f32_e32 v121, v121
	v_mfma_f32_32x32x16_bf16 v[80:95], v[132:135], v[168:171], v[80:95]
	ds_read_b128 v[132:135], v201 offset:20992
	v_exp_f32_e32 v122, v122
	v_exp_f32_e32 v123, v123
	s_waitcnt lgkmcnt(3)
	v_mfma_f32_32x32x16_bf16 v[64:79], v[188:191], v[172:175], v[64:79]
	v_exp_f32_e32 v124, v124
	v_exp_f32_e32 v125, v125
	v_mfma_f32_32x32x16_bf16 v[80:95], v[140:143], v[172:175], v[80:95]
	v_exp_f32_e32 v126, v126
	v_exp_f32_e32 v127, v127
	v_cvt_pk_bf16_f32 v140, v96, v97
	v_cvt_pk_bf16_f32 v141, v98, v99
	v_cvt_pk_bf16_f32 v142, v100, v101
	v_cvt_pk_bf16_f32 v143, v102, v103

; #define FLAS __attribute__((address_space(3)))
; #define FA_SB() __builtin_amdgcn_sched_barrier(0)
; #define FA_EXP2(J, PX, R) do { const float e0_ = __builtin_amdgcn_exp2f(PX[R]), e1_ = __builtin_amdgcn_exp2f(PX[(R) + 1]); ps += e0_; ps += e1_; PWN[(J) >> 2][(J) & 3] = cvtpk(e0_, e1_); } while (0)
; __device__ __forceinline__ void attn_unit_a(FLAS unsigned char* lds, const Unit u) {
;     ...
;         u32x4 vr[3];
; #pragma unroll
;         for (int m = 0; m < 3; ++m) vr[m] = FA_VFRAG(m);
;     ...
;         kf[0] = FA_KF(2, 0); kf[1] = FA_KF(2, 1); FA_EXP2(9, pC1, 2); FA_SB();
;         pN0 = __builtin_amdgcn_mfma_f32_32x32x16_bf16(kf[2], qr[1], pN0, 0, 0, 0); FA_EXP2(10, pC1, 4); FA_SB();
;         pN1 = __builtin_amdgcn_mfma_f32_32x32x16_bf16(kf[3], qr[1], pN1, 0, 0, 0); kf[2] = FA_KF(3, 0); kf[3] = FA_KF(3, 1); FA_EXP2(11, pC1, 6); FA_SB();
;         pN0 = __builtin_amdgcn_mfma_f32_32x32x16_bf16(kf[0], qr[2], pN0, 0, 0, 0); FA_EXP2(12, pC1, 8); FA_SB();
;         pN1 = __builtin_amdgcn_mfma_f32_32x32x16_bf16(kf[1], qr[2], pN1, 0, 0, 0); FA_EXP2(13, pC1, 10); FA_SB();
;         pN0 = __builtin_amdgcn_mfma_f32_32x32x16_bf16(kf[2], qr[3], pN0, 0, 0, 0); FA_EXP2(14, pC1, 12); FA_SB();
;         pN1 = __builtin_amdgcn_mfma_f32_32x32x16_bf16(kf[3], qr[3], pN1, 0, 0, 0); FA_EXP2(15, pC1, 14); FA_SB();
;     ...
;         lsum += ps; cbC = cbN;
;         if (i + 2 < NT) { *(FLAS u32x4*)(lds + LA_K + (i & 1) * KBUF + kdst) = kreg;
; #pragma unroll
;             for (int j = 0; j < 2; ++j) { *(FLAS u32x2*)(lds + LA_V + ((i + 2) & 3) * VBUF + vdst + j * 64 * VPITCH) = (u32x2){vreg[j].x, vreg[j].y}; *(FLAS u32x2*)(lds + LA_V + ((i + 2) & 3) * VBUF + vdst + j * 64 * VPITCH + 16) = (u32x2){vreg[j].z, vreg[j].w}; } }
.Lk2_o:
	ds_read_b128 v[128:131], v249
	ds_read_b128 v[132:135], v249 offset:512
	v_mfma_f32_32x32x16_bf16 v[96:111], v[192:195], v[164:167], v[96:111]
	v_exp_f32_e32 v84, v84
	v_exp_f32_e32 v85, v85
	v_mfma_f32_32x32x16_bf16 v[112:127], v[188:191], v[164:167], v[112:127]
	v_add_u32_e32 v204, s18, v245
	v_add_u32_e32 v205, 0x4000, v204
	v_add_u32_e32 v204, 0x6000, v204
	s_waitcnt vmcnt(2)
	ds_write_b128 v225, v[176:179] offset:8192
	s_waitcnt vmcnt(1)
	ds_write2_b64 v205, v[180:181], v[182:183] offset1:2
	s_waitcnt vmcnt(0)
	ds_write2_b64 v204, v[184:185], v[186:187] offset0:128 offset1:130
	s_add_i32 s12, s34, -1
	s_and_b32 s18, s12, 3
	s_mulk_i32 s18, 0x4800
	v_add_u32_e32 v200, s18, v251
	ds_read_b128 v[204:207], v250
	ds_read_b128 v[140:143], v250 offset:512
	ds_read_b128 v[136:139], v200 offset:25600
	v_exp_f32_e32 v86, v86
	v_exp_f32_e32 v87, v87
	s_waitcnt lgkmcnt(6)
	v_mfma_f32_32x32x16_bf16 v[96:111], v[128:131], v[168:171], v[96:111]
	ds_read_b128 v[128:131], v200 offset:16384
	v_exp_f32_e32 v88, v88
	v_exp_f32_e32 v89, v89
	v_mfma_f32_32x32x16_bf16 v[112:127], v[132:135], v[168:171], v[112:127]
	ds_read_b128 v[132:135], v200 offset:20992
	v_exp_f32_e32 v90, v90
	v_exp_f32_e32 v91, v91
	s_waitcnt lgkmcnt(3)
	v_mfma_f32_32x32x16_bf16 v[96:111], v[204:207], v[172:175], v[96:111]
	v_exp_f32_e32 v92, v92
	v_exp_f32_e32 v93, v93
	v_mfma_f32_32x32x16_bf16 v[112:127], v[140:143], v[172:175], v[112:127]
	v_exp_f32_e32 v94, v94
	v_exp_f32_e32 v95, v95
